# GQA steady loop: redundant NaN-canonicalizing v_max pairs and add-zero removed from the row-max / any() chain between QK and PV MFMAs (sec 7.12 style), nop pad re-derived (on top of v18)
# speedup vs baseline: 1.0079x; 1.0079x over previous
.LBB0_509:
	v_add_u32_e32 v182, s0, v220
	ds_read_b64_tr_b16 v[178:179], v182 offset:24576
	ds_read_b64_tr_b16 v[180:181], v182 offset:25088
	s_waitcnt lgkmcnt(9)
	v_mfma_f32_32x32x16_bf16 v[98:113], v[174:177], v[142:145], v[34:49]
	v_add_f32_e32 v82, v66, v67
	v_add_f32_e32 v82, v68, v82
	v_add_f32_e32 v82, v69, v82
	v_add_f32_e32 v82, v70, v82
	v_add_f32_e32 v82, v71, v82
	v_cvt_pk_bf16_f32 v134, v66, v67
	v_cvt_pk_bf16_f32 v135, v68, v69
	ds_read_b64_tr_b16 v[174:175], v182 offset:28672
	ds_read_b64_tr_b16 v[176:177], v182 offset:29184
	v_add_f32_e32 v66, v72, v82
	s_waitcnt lgkmcnt(10)
	v_mfma_f32_32x32x16_bf16 v[82:97], v[170:173], v[142:145], v[34:49]
	v_add_f32_e32 v66, v73, v66
	v_add_f32_e32 v66, v74, v66
	v_add_f32_e32 v114, v75, v66
	v_cvt_pk_bf16_f32 v136, v70, v71
	v_cvt_pk_bf16_f32 v137, v72, v73
	ds_read_b64_tr_b16 v[66:67], v182 offset:25600
	ds_read_b64_tr_b16 v[68:69], v182 offset:26112
	s_waitcnt lgkmcnt(11)
	v_mfma_f32_32x32x16_bf16 v[98:113], v[166:169], v[138:141], v[98:113]
	v_add_f32_e32 v70, v76, v114
	v_add_f32_e32 v70, v77, v70
	v_add_f32_e32 v70, v78, v70
	v_add_f32_e32 v114, v79, v70
	v_cvt_pk_bf16_f32 v126, v74, v75
	v_cvt_pk_bf16_f32 v127, v76, v77
	ds_read_b64_tr_b16 v[70:71], v182 offset:29696
	ds_read_b64_tr_b16 v[72:73], v182 offset:30208
	s_waitcnt lgkmcnt(12)
	v_mfma_f32_32x32x16_bf16 v[82:97], v[162:165], v[138:141], v[82:97]
	v_add_f32_e32 v74, v80, v114
	v_add_f32_e32 v74, v81, v74
	v_add_f32_e32 v74, v50, v74
	v_add_f32_e32 v114, v51, v74
	v_cvt_pk_bf16_f32 v128, v78, v79
	v_cvt_pk_bf16_f32 v129, v80, v81
	ds_read_b64_tr_b16 v[74:75], v182 offset:26624
	ds_read_b64_tr_b16 v[76:77], v182 offset:27136
	s_waitcnt lgkmcnt(13)
	v_mfma_f32_32x32x16_bf16 v[98:113], v[158:161], v[130:133], v[98:113]
	v_add_f32_e32 v78, v52, v114
	v_add_f32_e32 v78, v53, v78
	v_add_f32_e32 v78, v54, v78
	v_add_f32_e32 v78, v55, v78
	v_cvt_pk_bf16_f32 v118, v50, v51
	v_cvt_pk_bf16_f32 v119, v52, v53
	ds_read_b64_tr_b16 v[50:51], v182 offset:30720
	ds_read_b64_tr_b16 v[52:53], v182 offset:31232
	s_waitcnt lgkmcnt(14)
	v_mfma_f32_32x32x16_bf16 v[82:97], v[154:157], v[130:133], v[82:97]
	v_add_f32_e32 v78, v56, v78
	v_add_f32_e32 v78, v57, v78
	v_add_f32_e32 v78, v58, v78
	v_add_f32_e32 v78, v59, v78
	v_cvt_pk_bf16_f32 v120, v54, v55
	v_cvt_pk_bf16_f32 v121, v56, v57
	ds_read_b64_tr_b16 v[54:55], v182 offset:27648
	ds_read_b64_tr_b16 v[56:57], v182 offset:28160
	s_waitcnt lgkmcnt(14)
	v_mfma_f32_32x32x16_bf16 v[98:113], v[150:153], v[122:125], v[98:113]
	v_add_f32_e32 v78, v60, v78
	v_add_f32_e32 v78, v61, v78
	v_add_f32_e32 v78, v62, v78
	v_add_f32_e32 v78, v63, v78
	v_cvt_pk_bf16_f32 v114, v58, v59
	v_cvt_pk_bf16_f32 v115, v60, v61
	ds_read_b64_tr_b16 v[58:59], v182 offset:31744
	ds_read_b64_tr_b16 v[60:61], v182 offset:32256
	v_mfma_f32_32x32x16_bf16 v[82:97], v[146:149], v[122:125], v[82:97]
	v_add_f32_e32 v78, v64, v78
	v_add_f32_e32 v78, v65, v78
	v_cvt_pk_bf16_f32 v116, v62, v63
	v_cvt_pk_bf16_f32 v117, v64, v65
	v_lshl_add_u64 v[62:63], v[194:195], 0, s[60:61]
	s_add_i32 s0, s12, s14
	s_mov_b32 s1, m0
	s_mov_b32 m0, s0
	s_nop 0
	global_load_lds_dwordx4 v[62:63], off
	s_mov_b32 m0, s1
	v_lshl_add_u64 v[62:63], v[192:193], 0, s[60:61]
	s_add_i32 s0, s9, s16
	s_mov_b32 s1, m0
	s_mov_b32 m0, s0
	s_nop 0
	global_load_lds_dwordx4 v[62:63], off
	s_mov_b32 m0, s1
	v_max_f32_e32 v62, v98, v99
	v_max3_f32 v63, v100, v101, v83
	v_max3_f32 v62, v62, v82, v84
	v_max3_f32 v62, v62, v85, v102
	v_max3_f32 v63, v63, v104, v105
	v_max3_f32 v62, v62, v103, v86
	v_max3_f32 v63, v63, v88, v89
	v_max3_f32 v62, v62, v87, v106
	v_max3_f32 v63, v63, v108, v109
	v_max3_f32 v62, v62, v107, v90
	v_max3_f32 v63, v63, v92, v93
	v_max3_f32 v62, v62, v91, v110
	v_max3_f32 v63, v63, v112, v113
	v_max3_f32 v62, v62, v111, v94
	v_max3_f32 v63, v63, v96, v97
	v_max3_f32 v62, v62, v95, v63
	v_mov_b32_e32 v63, v62
	s_nop 1
	v_permlane32_swap_b32_e32 v62, v63
	v_max_f32_e32 v62, v62, v63
	v_cmp_lt_f32_e32 vcc, s63, v62
	s_cmp_lg_u64 vcc, 0
	v_add_f32_e32 v223, v223, v78
	s_cselect_b64 s[6:7], -1, 0
	s_cbranch_vccnz .LBB0_517

.LBB0_512:
	s_add_i32 s0, s9, 0x2000
	s_cmpk_lg_i32 s9, 0x4000
	s_cselect_b32 s13, s0, 0
	v_add_u32_e32 v182, s12, v220
	ds_read_b64_tr_b16 v[150:151], v182 offset:24576
	ds_read_b64_tr_b16 v[152:153], v182 offset:25088
	s_waitcnt lgkmcnt(9)
	v_mfma_f32_32x32x16_bf16 v[66:81], v[62:65], v[142:145], v[34:49]
	v_add_f32_e32 v50, v98, v99
	v_add_f32_e32 v50, v100, v50
	v_add_f32_e32 v50, v101, v50
	v_add_f32_e32 v50, v102, v50
	v_add_f32_e32 v50, v103, v50
	v_cvt_pk_bf16_f32 v134, v98, v99
	v_cvt_pk_bf16_f32 v135, v100, v101
	ds_read_b64_tr_b16 v[146:147], v182 offset:28672
	ds_read_b64_tr_b16 v[148:149], v182 offset:29184
	v_add_f32_e32 v50, v104, v50
	v_add_f32_e32 v50, v105, v50
	v_add_f32_e32 v50, v106, v50
	v_add_f32_e32 v114, v107, v50
	s_waitcnt lgkmcnt(10)
	v_mfma_f32_32x32x16_bf16 v[50:65], v[174:177], v[142:145], v[34:49]
	v_cvt_pk_bf16_f32 v136, v102, v103
	v_cvt_pk_bf16_f32 v137, v104, v105
	ds_read_b64_tr_b16 v[98:99], v182 offset:25600
	ds_read_b64_tr_b16 v[100:101], v182 offset:26112
	s_waitcnt lgkmcnt(11)
	v_mfma_f32_32x32x16_bf16 v[66:81], v[178:181], v[138:141], v[66:81]
	v_add_f32_e32 v102, v108, v114
	v_add_f32_e32 v102, v109, v102
	v_add_f32_e32 v102, v110, v102
	v_add_f32_e32 v114, v111, v102
	v_cvt_pk_bf16_f32 v126, v106, v107
	v_cvt_pk_bf16_f32 v127, v108, v109
	ds_read_b64_tr_b16 v[102:103], v182 offset:29696
	ds_read_b64_tr_b16 v[104:105], v182 offset:30208
	s_waitcnt lgkmcnt(12)
	v_mfma_f32_32x32x16_bf16 v[50:65], v[170:173], v[138:141], v[50:65]
	v_add_f32_e32 v106, v112, v114
	v_add_f32_e32 v106, v113, v106
	v_add_f32_e32 v106, v82, v106
	v_add_f32_e32 v114, v83, v106
	v_cvt_pk_bf16_f32 v128, v110, v111
	v_cvt_pk_bf16_f32 v129, v112, v113
	ds_read_b64_tr_b16 v[106:107], v182 offset:26624
	ds_read_b64_tr_b16 v[108:109], v182 offset:27136
	s_waitcnt lgkmcnt(13)
	v_mfma_f32_32x32x16_bf16 v[66:81], v[166:169], v[130:133], v[66:81]
	v_add_f32_e32 v110, v84, v114
	v_add_f32_e32 v110, v85, v110
	v_add_f32_e32 v110, v86, v110
	v_add_f32_e32 v110, v87, v110
	v_cvt_pk_bf16_f32 v118, v82, v83
	v_cvt_pk_bf16_f32 v119, v84, v85
	ds_read_b64_tr_b16 v[82:83], v182 offset:30720
	ds_read_b64_tr_b16 v[84:85], v182 offset:31232
	s_waitcnt lgkmcnt(14)
	v_mfma_f32_32x32x16_bf16 v[50:65], v[162:165], v[130:133], v[50:65]
	v_add_f32_e32 v110, v88, v110
	v_add_f32_e32 v110, v89, v110
	v_add_f32_e32 v110, v90, v110
	v_add_f32_e32 v110, v91, v110
	v_cvt_pk_bf16_f32 v120, v86, v87
	v_cvt_pk_bf16_f32 v121, v88, v89
	ds_read_b64_tr_b16 v[86:87], v182 offset:27648
	ds_read_b64_tr_b16 v[88:89], v182 offset:28160
	s_waitcnt lgkmcnt(14)
	v_mfma_f32_32x32x16_bf16 v[66:81], v[158:161], v[122:125], v[66:81]
	v_add_f32_e32 v110, v92, v110
	v_add_f32_e32 v110, v93, v110
	v_add_f32_e32 v110, v94, v110
	v_add_f32_e32 v110, v95, v110
	v_cvt_pk_bf16_f32 v114, v90, v91
	v_cvt_pk_bf16_f32 v115, v92, v93
	ds_read_b64_tr_b16 v[90:91], v182 offset:31744
	ds_read_b64_tr_b16 v[92:93], v182 offset:32256
	v_mfma_f32_32x32x16_bf16 v[50:65], v[154:157], v[122:125], v[50:65]
	v_add_f32_e32 v110, v96, v110
	v_add_f32_e32 v110, v97, v110
	v_cvt_pk_bf16_f32 v116, v94, v95
	v_cvt_pk_bf16_f32 v117, v96, v97
	v_max_f32_e32 v94, v66, v67
	s_nop 6
	v_max3_f32 v95, v68, v69, v51
	v_max3_f32 v94, v94, v50, v52
	v_max3_f32 v94, v94, v53, v70
	v_max3_f32 v95, v95, v72, v73
	v_max3_f32 v94, v94, v71, v54
	v_max3_f32 v95, v95, v56, v57
	v_max3_f32 v94, v94, v55, v74
	v_max3_f32 v95, v95, v76, v77
	v_max3_f32 v94, v94, v75, v58
	v_max3_f32 v95, v95, v60, v61
	v_max3_f32 v94, v94, v59, v78
	v_max3_f32 v95, v95, v80, v81
	v_max3_f32 v94, v94, v79, v62
	v_max3_f32 v95, v95, v64, v65
	v_max3_f32 v94, v94, v63, v95
	v_mov_b32_e32 v95, v94
	s_nop 1
	v_permlane32_swap_b32_e32 v94, v95
	s_add_i32 s0, s9, s14
	s_mov_b32 s1, m0
	s_mov_b32 m0, s0
	s_nop 0
	global_load_lds_dwordx4 v[194:195], off
	s_mov_b32 m0, s1
	v_max_f32_e32 v94, v94, v95
	s_add_i32 s0, s13, s16
	s_mov_b32 s1, m0
	s_mov_b32 m0, s0
	s_nop 0
	global_load_lds_dwordx4 v[192:193], off
	s_mov_b32 m0, s1
	v_cmp_lt_f32_e32 vcc, s63, v94
	s_cmp_lg_u64 vcc, 0
	v_add_f32_e32 v223, v223, v110
	s_cselect_b64 s[6:7], -1, 0
	s_cbranch_vccnz .LBB0_520
